# as v44 with larger idle-window conversion budgets: in-proj tail 3 iterations, gate-up tail 2
# speedup vs baseline: 1.0023x; 1.0023x over previous
; #define LAS __attribute__((address_space(3)))
; __device__ __forceinline__ void convert_layer_static(const PT& a, LAS unsigned char* lds, int l, int gw, int NGW, int wave, int lane, int r_end = IT_LAYER) {
;     for (int r = 2 * gw; r < r_end; r += 2 * NGW) cv_pair(a, lds, l, r, wave, lane);
; }
; __device__ __forceinline__ void prologue_a(const PT& a, LAS unsigned char* lds) {
;     ...
;     convert_layer_static(a, lds, 0, gw, NGW, wave, lane);
;     for (int cl_ = 1; cl_ < DEPTH; ++cl_) convert_layer_static(a, lds, cl_, gw, NGW, wave, lane, CV_PRO_ITEMS);
.LBB0_110:
	s_or_b64 exec, exec, s[12:13]
	v_lshl_add_u32 v2, v74, 2, v115
	v_add_u32_e32 v3, v115, v113
	s_mov_b32 s13, 0
	v_lshl_add_u32 v113, v67, 2, v3
	v_lshl_add_u32 v115, v69, 2, v3
	v_lshl_add_u32 v117, v97, 2, v3
	v_lshl_add_u32 v119, v99, 2, v3
	s_mov_b32 s18, 1
	s_lshl_b32 s42, s17, 5
	s_movk_i32 s43, 0x393f
	s_movk_i32 s44, 0x453f
	s_movk_i32 s45, 0x4d3f
	s_movk_i32 s46, 0x793f
	s_movk_i32 s47, 0x15ff
	s_movk_i32 s48, 0xba3
	s_movk_i32 s49, 0x1600
	s_movk_i32 s50, 0x3ff
	v_mov_b32_e32 v79, 0
	s_mov_b64 s[20:21], 0xea00000
	s_mov_b32 s51, 0x478bbced
	s_movk_i32 s52, 0x9f
	s_movk_i32 s53, 0x109
	v_add_u32_e32 v121, v2, v121
	v_lshlrev_b64 v[76:77], 1, v[76:77]
	s_mov_b32 s54, 0x533f
	v_readlane_b32 s100, v252, 4
	s_cmp_eq_u32 s100, 0x100
	s_cselect_b32 s54, s54, 0x8f3f
	v_mov_b32_e32 v123, 0xea00
	v_mov_b32_e32 v125, 5
	v_mov_b32_e32 v128, 0x23a40
	v_mov_b32_e32 v129, 0x23a38
	v_mov_b32_e32 v130, 6
	v_mov_b32_e32 v131, 0x80
	v_mov_b32_e32 v132, 0x23a20
	v_mov_b32_e32 v133, 0x23a18
	v_mov_b32_e32 v134, 0x23a10
	s_branch .LBB0_112

; __device__ __forceinline__ int opaque_tid() { int t = threadIdx.x; asm volatile("" : "+v"(t)); return t; }
;     for (int it = 0; it < budget; ++it) {
;         unsigned r = 0; if (lane == 0) r = __hip_atomic_fetch_add(ctr, 2u, __ATOMIC_RELAXED, __HIP_MEMORY_SCOPE_AGENT);
;         r = (unsigned)__builtin_amdgcn_readfirstlane((int)r) + (unsigned)CV_PRO_ITEMS;
;         if (r >= (unsigned)IT_LAYER) break;
;         cv_pair(a, lds, l, (int)r, wave, lane);
;     }
; }
; __global__ void __launch_bounds__(NTHREADS, 2) mk_fwd(Args args) {
;     ...
;             if (l + 1 < DEPTH && !(G >= 256 && bid < 128)) { __syncthreads(); const int tid_ = opaque_tid(); convert_layer_queue(pt, lds, l + 1, cvq, tid_ >> 6, tid_ & 63); }
.LBB0_560:
	v_readlane_b32 s0, v252, 4
	s_cmp_lg_u32 s0, 0x100
	s_cbranch_scc1 .LcvqA_ret
	v_readlane_b32 s0, v252, 0
	v_readlane_b32 s36, v255, 0
	s_cmp_lt_u32 s0, 64
	s_cbranch_scc1 .LcvqA_ret
	s_cmp_gt_u32 s36, 2
	s_cbranch_scc1 .LcvqA_ret
	s_mov_b32 s64, s36
	v_readlane_b32 s0, v254, 53
	v_readlane_b32 s1, v254, 54
	s_mov_b32 s3, s1
	s_lshl_b32 s2, s36, 6
	s_lshl_b64 s[0:1], s[2:3], 2
	v_readlane_b32 s4, v254, 60
	v_readlane_b32 s5, v254, 61
	s_add_u32 s0, s4, s0
	s_addc_u32 s1, s5, s1
	s_add_u32 s0, s0, 0x8000
	s_addc_u32 s1, s1, 0
	s_add_i32 s2, s36, 1
	s_mul_hi_u32 s33, s2, 0x2c00000
	s_mul_i32 s34, s2, 0x2c00000
	s_mul_hi_u32 s35, s2, 0x1600000
	s_mul_i32 s50, s2, 0x1600000
	s_lshl_b32 s6, s2, 11
	s_mov_b32 s7, s3
	s_lshl_b64 s[8:9], s[2:3], 24
	s_lshl_b64 s[10:11], s[2:3], 23
	s_mul_hi_u32 s51, s2, 0xc00000
	s_mul_i32 s52, s2, 0xc00000
	s_mul_hi_u32 s53, s2, 0x7280000
	s_mul_i32 s54, s2, 0x7280000
	s_mul_hi_u32 s55, s2, 0x3a00000
	v_writelane_b32 v254, s2, 53
	v_mov_b32_e32 v2, v0
	s_mul_i32 s56, s2, 0x3a00000
	v_writelane_b32 v254, s3, 54
	s_waitcnt vmcnt(0) lgkmcnt(0)
	s_barrier
	s_movk_i32 s2, 0x4200
	v_lshrrev_b32_e32 v1, 6, v2
	v_and_b32_e32 v3, 63, v2
	v_readfirstlane_b32 s100, v1
	v_readlane_b32 s101, v252, 0
	s_sub_u32 s101, s101, 64
	s_lshl_b32 s101, s101, 3
	s_add_u32 s100, s100, s101
	s_lshl_b32 s100, s100, 1
	s_add_u32 s100, s100, 0x0
	v_mul_lo_u32 v1, v1, s2
	v_cmp_eq_u32_e64 s[40:41], 0, v3
	v_add_u32_e32 v3, 0, v1
	v_lshlrev_b32_e32 v1, 2, v2
	v_and_b32_e32 v66, 28, v1
	v_bfe_u32 v1, v2, 3, 3
	v_lshlrev_b32_e32 v2, 3, v2
	v_and_b32_e32 v68, 56, v2
	v_lshl_add_u32 v4, v66, 2, v3
	v_mul_u32_u24_e32 v5, 0x84, v1
	v_mul_u32_u24_e32 v2, 0x84, v68
	v_lshlrev_b32_e32 v6, 2, v1
	v_or_b32_e32 v67, 8, v1
	v_or_b32_e32 v69, 16, v1
	v_or_b32_e32 v71, 24, v1
	v_or_b32_e32 v73, 32, v1
	v_or_b32_e32 v75, 40, v1
	v_or_b32_e32 v77, 48, v1
	v_or_b32_e32 v79, 56, v1
	v_add3_u32 v81, v3, v2, v6
	s_mov_b32 s57, 0x3
	v_add_u32_e32 v83, v4, v5
	s_branch .LcvqA_1381

;     __device__ __forceinline__ const float* in(int i) const { return (const float*)(const GAS float*)raw(i); }
;     __device__ __forceinline__ unsigned char* ws() const { return (unsigned char*)(GAS unsigned char*)raw(N_INPUTS + 1); }
; __device__ __forceinline__ CvItem cv_decode(const PT& a, int l, int r) {
;     unsigned char* ws = a.ws(); CvItem it;
;     if (r < IT_WIN) { const int kb = r / 458, nb = r % 458, n0 = nb * 32;
;         int drow; if (n0 < 2048) drow = n0; else if (n0 < 5120) drow = NIN_MAIN + (n0 - 2048); else if (n0 < 8512) drow = 2048 + (n0 - 5120); else drow = 5632 + (n0 - 8512);
;         it = CvItem{a.in(I_W_IN) + (size_t)l * D * NIN, NIN, kb * 64, n0, (bf16_t*)(ws + WS_WIN + l * WIN_L), D, drow, a.in(I_NORM_MIX_G) + l * D}; return it; }
;     r -= IT_WIN;
;     if (r < 3 * IT_BR) { const int br = r / IT_BR; r -= br * IT_BR; const int kb = r / 64, nb = r % 64;
;         it = CvItem{a.in(br == 0 ? I_W_BR_A : (br == 1 ? I_W_BR_B : I_W_BR_C)) + (size_t)l * 1024 * D, D, kb * 64, nb * 32, (bf16_t*)(ws + WS_WBR + l * WBR_L) + (size_t)br * D * 1024, 1024, nb * 32, nullptr}; return it; }
;     r -= 3 * IT_BR;
;     if (r < IT_OUT) { const int kb = r / 64, nb = r % 64;
;         it = CvItem{a.in(I_W_OUT) + (size_t)l * D * D, D, kb * 64, nb * 32, (bf16_t*)(ws + WS_WOUT + l * WOUT_L), D, nb * 32, nullptr}; return it; }
;     r -= IT_OUT;
;     if (r < 2 * IT_GU) { const int up = r / IT_GU; r -= up * IT_GU; const int kb = r / 176, nb = r % 176, n0 = nb * 32;
;         it = CvItem{a.in(up ? I_W_FFN_UP : I_W_FFN_GATE) + (size_t)l * D * DFF, DFF, kb * 64, n0, (bf16_t*)(ws + WS_WGU + l * WGU_L), D, 256 * (n0 / 128) + (n0 % 128) + 128 * up, a.in(I_NORM_FFN_G) + l * D}; return it; }
;     r -= 2 * IT_GU;
;     { const int kb = r / 64, nb = r % 64;
;       it = CvItem{a.in(I_W_FFN_DOWN) + (size_t)l * DFF * D, D, kb * 64, nb * 32, (bf16_t*)(ws + WS_WDN + l * WDN_L), DFF, nb * 32, nullptr}; }
;     for (int it = 0; it < budget; ++it) {
;         unsigned r = 0; if (lane == 0) r = __hip_atomic_fetch_add(ctr, 2u, __ATOMIC_RELAXED, __HIP_MEMORY_SCOPE_AGENT);
;         r = (unsigned)__builtin_amdgcn_readfirstlane((int)r) + (unsigned)CV_PRO_ITEMS;
;         if (r >= (unsigned)IT_LAYER) break;
;         cv_pair(a, lds, l, (int)r, wave, lane);
.LcvqA_1381:
	s_mov_b32 s24, s100
	s_add_u32 s100, s100, 0xc00
	s_add_i32 s24, s24, 0xffffc400
	s_cmp_lt_u32 s24, 0xffff70c0
	s_mov_b64 s[2:3], -1
	s_cbranch_scc1 .LcvqA_1380
	v_mov_b32_e32 v2, 0x23a60
	s_add_i32 s15, s24, 0x8f40
	v_add_u32_e32 v2, 0, v2
	ds_read_b64 v[2:3], v2
	s_cmpk_gt_u32 s15, 0x393f
	s_waitcnt lgkmcnt(0)
	v_readfirstlane_b32 s20, v3
	v_readfirstlane_b32 s21, v2
	s_cbranch_scc0 .LcvqA_1399
	s_cmpk_gt_u32 s15, 0x453f
	s_cbranch_scc0 .LcvqA_1396
	s_cmpk_gt_u32 s15, 0x4d3f
	s_mov_b64 s[18:19], -1
	s_cbranch_scc0 .LcvqA_1393
	s_cmpk_gt_u32 s15, 0x793f
	s_cbranch_scc0 .LcvqA_1391
	v_mov_b32_e32 v2, 0x23a48
	s_and_b32 s2, s15, 0x7fffffc0
	v_add_u32_e32 v2, 0, v2
	ds_read_b64 v[2:3], v2
	s_add_i32 s14, s2, 0xffff86c0
	s_waitcnt lgkmcnt(0)
	v_readfirstlane_b32 s3, v2
	v_readfirstlane_b32 s2, v3
	s_add_u32 s30, s3, s34
	s_addc_u32 s31, s2, s33
	s_lshl_b32 s2, s15, 5
	s_and_b32 s25, s2, 0x7e0
	s_add_u32 s2, s21, s50
	s_addc_u32 s3, s20, s35
	s_add_u32 s12, s2, 0x1ea00000
	s_addc_u32 s13, s3, 0
	s_mov_b64 s[2:3], 0

; __device__ __forceinline__ int opaque_tid() { int t = threadIdx.x; asm volatile("" : "+v"(t)); return t; }
;     for (int it = 0; it < budget; ++it) {
;         unsigned r = 0; if (lane == 0) r = __hip_atomic_fetch_add(ctr, 2u, __ATOMIC_RELAXED, __HIP_MEMORY_SCOPE_AGENT);
;         r = (unsigned)__builtin_amdgcn_readfirstlane((int)r) + (unsigned)CV_PRO_ITEMS;
;         if (r >= (unsigned)IT_LAYER) break;
;         cv_pair(a, lds, l, (int)r, wave, lane);
;     }
; }
; __global__ void __launch_bounds__(NTHREADS, 2) mk_fwd(Args args) {
;     ...
;             if (l + 1 < DEPTH && !(G >= 256 && bid < 128)) { __syncthreads(); const int tid_ = opaque_tid(); convert_layer_queue(pt, lds, l + 1, cvq, tid_ >> 6, tid_ & 63); }
.LBB0_1377:
	s_cmp_eq_u32 s64, 3
	v_readlane_b32 s2, v253, 61
	s_cselect_b64 s[0:1], -1, 0
	v_readlane_b32 s3, v253, 62
	s_or_b64 s[0:1], s[2:3], s[0:1]
	v_readlane_b32 s2, v252, 4
	s_cmp_lg_u32 s2, 0x100
	s_cselect_b64 s[2:3], -1, 0
	s_or_b64 s[0:1], s[0:1], s[2:3]
	v_readlane_b32 s28, v254, 55
	s_mov_b32 s36, s64
	s_and_b64 vcc, exec, s[0:1]
	v_readlane_b32 s29, v254, 56
	s_cbranch_vccnz .LBB0_1470
	v_readlane_b32 s0, v254, 53
	v_readlane_b32 s1, v254, 54
	s_mov_b32 s3, s1
	s_lshl_b32 s2, s36, 6
	s_lshl_b64 s[0:1], s[2:3], 2
	v_readlane_b32 s4, v254, 60
	v_readlane_b32 s5, v254, 61
	s_add_u32 s0, s4, s0
	s_addc_u32 s1, s5, s1
	s_add_u32 s0, s0, 0x8000
	s_addc_u32 s1, s1, 0
	s_add_i32 s2, s36, 1
	s_mul_hi_u32 s33, s2, 0x2c00000
	s_mul_i32 s34, s2, 0x2c00000
	s_mul_hi_u32 s35, s2, 0x1600000
	s_mul_i32 s50, s2, 0x1600000
	s_lshl_b32 s6, s2, 11
	s_mov_b32 s7, s3
	s_lshl_b64 s[8:9], s[2:3], 24
	s_lshl_b64 s[10:11], s[2:3], 23
	s_mul_hi_u32 s51, s2, 0xc00000
	s_mul_i32 s52, s2, 0xc00000
	s_mul_hi_u32 s53, s2, 0x7280000
	s_mul_i32 s54, s2, 0x7280000
	s_mul_hi_u32 s55, s2, 0x3a00000
	v_writelane_b32 v254, s2, 53
	v_mov_b32_e32 v2, v0
	s_mul_i32 s56, s2, 0x3a00000
	v_writelane_b32 v254, s3, 54
	s_waitcnt vmcnt(0) lgkmcnt(0)
	s_barrier
	s_movk_i32 s2, 0x4200
	v_lshrrev_b32_e32 v1, 6, v2
	v_and_b32_e32 v3, 63, v2
	v_readfirstlane_b32 s100, v1
	v_readlane_b32 s101, v252, 0
	s_sub_u32 s101, s101, 128
	s_lshl_b32 s101, s101, 3
	s_add_u32 s100, s100, s101
	s_lshl_b32 s100, s100, 1
	s_add_u32 s100, s100, 0x2400
	v_mul_lo_u32 v1, v1, s2
	v_cmp_eq_u32_e64 s[40:41], 0, v3
	v_add_u32_e32 v3, 0, v1
	v_lshlrev_b32_e32 v1, 2, v2
	v_and_b32_e32 v66, 28, v1
	v_bfe_u32 v1, v2, 3, 3
	v_lshlrev_b32_e32 v2, 3, v2
	v_and_b32_e32 v68, 56, v2
	v_lshl_add_u32 v4, v66, 2, v3
	v_mul_u32_u24_e32 v5, 0x84, v1
	v_mul_u32_u24_e32 v2, 0x84, v68
	v_lshlrev_b32_e32 v6, 2, v1
	v_or_b32_e32 v67, 8, v1
	v_or_b32_e32 v69, 16, v1
	v_or_b32_e32 v71, 24, v1
	v_or_b32_e32 v73, 32, v1
	v_or_b32_e32 v75, 40, v1
	v_or_b32_e32 v77, 48, v1
	v_or_b32_e32 v79, 56, v1
	v_add3_u32 v81, v3, v2, v6
	s_mov_b32 s57, 0x1
	v_add_u32_e32 v83, v4, v5
	s_branch .LBB0_1381

;     __device__ __forceinline__ const float* in(int i) const { return (const float*)(const GAS float*)raw(i); }
;     __device__ __forceinline__ unsigned char* ws() const { return (unsigned char*)(GAS unsigned char*)raw(N_INPUTS + 1); }
; __device__ __forceinline__ CvItem cv_decode(const PT& a, int l, int r) {
;     unsigned char* ws = a.ws(); CvItem it;
;     if (r < IT_WIN) { const int kb = r / 458, nb = r % 458, n0 = nb * 32;
;         int drow; if (n0 < 2048) drow = n0; else if (n0 < 5120) drow = NIN_MAIN + (n0 - 2048); else if (n0 < 8512) drow = 2048 + (n0 - 5120); else drow = 5632 + (n0 - 8512);
;         it = CvItem{a.in(I_W_IN) + (size_t)l * D * NIN, NIN, kb * 64, n0, (bf16_t*)(ws + WS_WIN + l * WIN_L), D, drow, a.in(I_NORM_MIX_G) + l * D}; return it; }
;     r -= IT_WIN;
;     if (r < 3 * IT_BR) { const int br = r / IT_BR; r -= br * IT_BR; const int kb = r / 64, nb = r % 64;
;         it = CvItem{a.in(br == 0 ? I_W_BR_A : (br == 1 ? I_W_BR_B : I_W_BR_C)) + (size_t)l * 1024 * D, D, kb * 64, nb * 32, (bf16_t*)(ws + WS_WBR + l * WBR_L) + (size_t)br * D * 1024, 1024, nb * 32, nullptr}; return it; }
;     r -= 3 * IT_BR;
;     if (r < IT_OUT) { const int kb = r / 64, nb = r % 64;
;         it = CvItem{a.in(I_W_OUT) + (size_t)l * D * D, D, kb * 64, nb * 32, (bf16_t*)(ws + WS_WOUT + l * WOUT_L), D, nb * 32, nullptr}; return it; }
;     r -= IT_OUT;
;     if (r < 2 * IT_GU) { const int up = r / IT_GU; r -= up * IT_GU; const int kb = r / 176, nb = r % 176, n0 = nb * 32;
;         it = CvItem{a.in(up ? I_W_FFN_UP : I_W_FFN_GATE) + (size_t)l * D * DFF, DFF, kb * 64, n0, (bf16_t*)(ws + WS_WGU + l * WGU_L), D, 256 * (n0 / 128) + (n0 % 128) + 128 * up, a.in(I_NORM_FFN_G) + l * D}; return it; }
;     r -= 2 * IT_GU;
;     { const int kb = r / 64, nb = r % 64;
;       it = CvItem{a.in(I_W_FFN_DOWN) + (size_t)l * DFF * D, D, kb * 64, nb * 32, (bf16_t*)(ws + WS_WDN + l * WDN_L), DFF, nb * 32, nullptr}; }
;     for (int it = 0; it < budget; ++it) {
;         unsigned r = 0; if (lane == 0) r = __hip_atomic_fetch_add(ctr, 2u, __ATOMIC_RELAXED, __HIP_MEMORY_SCOPE_AGENT);
;         r = (unsigned)__builtin_amdgcn_readfirstlane((int)r) + (unsigned)CV_PRO_ITEMS;
;         if (r >= (unsigned)IT_LAYER) break;
;         cv_pair(a, lds, l, (int)r, wave, lane);
.LBB0_1381:
	s_mov_b32 s24, s100
	s_add_u32 s100, s100, 0x800
	s_add_i32 s24, s24, 0xffffc400
	s_cmp_lt_u32 s24, 0xffff70c0
	s_mov_b64 s[2:3], -1
	s_cbranch_scc1 .LBB0_1380
	v_mov_b32_e32 v2, 0x23a60
	s_add_i32 s15, s24, 0x8f40
	v_add_u32_e32 v2, 0, v2
	ds_read_b64 v[2:3], v2
	s_cmpk_gt_u32 s15, 0x393f
	s_waitcnt lgkmcnt(0)
	v_readfirstlane_b32 s20, v3
	v_readfirstlane_b32 s21, v2
	s_cbranch_scc0 .LBB0_1399
	s_cmpk_gt_u32 s15, 0x453f
	s_cbranch_scc0 .LBB0_1396
	s_cmpk_gt_u32 s15, 0x4d3f
	s_mov_b64 s[18:19], -1
	s_cbranch_scc0 .LBB0_1393
	s_cmpk_gt_u32 s15, 0x793f
	s_cbranch_scc0 .LBB0_1391
	v_mov_b32_e32 v2, 0x23a48
	s_and_b32 s2, s15, 0x7fffffc0
	v_add_u32_e32 v2, 0, v2
	ds_read_b64 v[2:3], v2
	s_add_i32 s14, s2, 0xffff86c0
	s_waitcnt lgkmcnt(0)
	v_readfirstlane_b32 s3, v2
	v_readfirstlane_b32 s2, v3
	s_add_u32 s30, s3, s34
	s_addc_u32 s31, s2, s33
	s_lshl_b32 s2, s15, 5
	s_and_b32 s25, s2, 0x7e0
	s_add_u32 s2, s21, s50
	s_addc_u32 s3, s20, s35
	s_add_u32 s12, s2, 0x1ea00000
	s_addc_u32 s13, s3, 0
	s_mov_b64 s[2:3], 0

; __device__ __forceinline__ int opaque_tid() { int t = threadIdx.x; asm volatile("" : "+v"(t)); return t; }
;     for (int it = 0; it < budget; ++it) {
;         unsigned r = 0; if (lane == 0) r = __hip_atomic_fetch_add(ctr, 2u, __ATOMIC_RELAXED, __HIP_MEMORY_SCOPE_AGENT);
;         r = (unsigned)__builtin_amdgcn_readfirstlane((int)r) + (unsigned)CV_PRO_ITEMS;
;         if (r >= (unsigned)IT_LAYER) break;
;         cv_pair(a, lds, l, (int)r, wave, lane);
;     }
; }
; __global__ void __launch_bounds__(NTHREADS, 2) mk_fwd(Args args) {
;     ...
;             if (l + 1 < DEPTH && !(G >= 256 && bid < 128)) { __syncthreads(); const int tid_ = opaque_tid(); convert_layer_queue(pt, lds, l + 1, cvq, tid_ >> 6, tid_ & 63); }
.LBB0_1843:
	v_readlane_b32 s2, v252, 4
	s_cmp_lg_u32 s2, 0x100
	s_cbranch_scc1 .LcvqB_skip
	v_readlane_b32 s2, v252, 0
	s_cmp_lt_u32 s2, 128
	s_cbranch_scc1 .LcvqB_skip
	s_cmp_gt_u32 s36, 2
	s_cbranch_scc1 .LcvqB_skip
	v_writelane_b32 v255, s0, 8
	v_writelane_b32 v255, s1, 9
	v_writelane_b32 v255, s40, 10
	v_writelane_b32 v255, s41, 11
	s_mov_b32 s64, s36
	v_readlane_b32 s0, v254, 53
	v_readlane_b32 s1, v254, 54
	s_mov_b32 s3, s1
	s_lshl_b32 s2, s36, 6
	s_lshl_b64 s[0:1], s[2:3], 2
	v_readlane_b32 s4, v254, 60
	v_readlane_b32 s5, v254, 61
	s_add_u32 s0, s4, s0
	s_addc_u32 s1, s5, s1
	s_add_u32 s0, s0, 0x8000
	s_addc_u32 s1, s1, 0
	s_add_i32 s2, s36, 1
	s_mul_hi_u32 s33, s2, 0x2c00000
	s_mul_i32 s34, s2, 0x2c00000
	s_mul_hi_u32 s35, s2, 0x1600000
	s_mul_i32 s50, s2, 0x1600000
	s_lshl_b32 s6, s2, 11
	s_mov_b32 s7, s3
	s_lshl_b64 s[8:9], s[2:3], 24
	s_lshl_b64 s[10:11], s[2:3], 23
	s_mul_hi_u32 s51, s2, 0xc00000
	s_mul_i32 s52, s2, 0xc00000
	s_mul_hi_u32 s53, s2, 0x7280000
	s_mul_i32 s54, s2, 0x7280000
	s_mul_hi_u32 s55, s2, 0x3a00000
	v_writelane_b32 v254, s2, 53
	v_mov_b32_e32 v2, v0
	s_mul_i32 s56, s2, 0x3a00000
	v_writelane_b32 v254, s3, 54
	s_waitcnt vmcnt(0) lgkmcnt(0)
	s_barrier
	s_movk_i32 s2, 0x4200
	v_lshrrev_b32_e32 v1, 6, v2
	v_and_b32_e32 v3, 63, v2
	v_readfirstlane_b32 s100, v1
	v_readlane_b32 s101, v252, 0
	s_sub_u32 s101, s101, 128
	s_lshl_b32 s101, s101, 3
	s_add_u32 s100, s100, s101
	s_lshl_b32 s100, s100, 1
	s_add_u32 s100, s100, 0x2c00
	v_mul_lo_u32 v1, v1, s2
	v_cmp_eq_u32_e64 s[40:41], 0, v3
	v_add_u32_e32 v3, 0, v1
	v_lshlrev_b32_e32 v1, 2, v2
	v_and_b32_e32 v66, 28, v1
	v_bfe_u32 v1, v2, 3, 3
	v_lshlrev_b32_e32 v2, 3, v2
	v_and_b32_e32 v68, 56, v2
	v_lshl_add_u32 v4, v66, 2, v3
	v_mul_u32_u24_e32 v5, 0x84, v1
	v_mul_u32_u24_e32 v2, 0x84, v68
	v_lshlrev_b32_e32 v6, 2, v1
	v_or_b32_e32 v67, 8, v1
	v_or_b32_e32 v69, 16, v1
	v_or_b32_e32 v71, 24, v1
	v_or_b32_e32 v73, 32, v1
	v_or_b32_e32 v75, 40, v1
	v_or_b32_e32 v77, 48, v1
	v_or_b32_e32 v79, 56, v1
	v_add3_u32 v81, v3, v2, v6
	s_mov_b32 s57, 0x2
	v_add_u32_e32 v83, v4, v5
	s_branch .LcvqB_1381
